# v052 + mLSTM n-state update: 8 serialized LDS partial-sum reads issued together (same add order)
# baseline (speedup 1.0000x reference)
; #define LAS __attribute__((address_space(3)))
; DI void phase_mlstm(const Params& p, unsigned char* shm, const int vb) {
;     ...
;             const float d_last = dec[63];
;             if (threadIdx.x < 256) { const int tid = threadIdx.x; float a = 0.f;
; #pragma unroll
;                 for (int g = 0; g < 16; ++g) a += *(const LAS float*)(lds + PNB + g * 1024 + tid * 4);
;                 n_s[tid] = d_last * n_s[tid] + a; }
.LBB0_404:
	v_mov_b32_e32 v128, s86
	ds_read_b32 v168, v128
	s_and_saveexec_b64 s[2:3], s[42:43]
	s_cbranch_execz .LBB0_406
	v_add_u32_e32 v128, 0, v172
	v_add_u32_e32 v130, 0x1e000, v128
	ds_read2st64_b32 v[202:203], v130 offset1:4
	ds_read2st64_b32 v[204:205], v130 offset0:8 offset1:12
	ds_read2st64_b32 v[206:207], v130 offset0:16 offset1:20
	ds_read2st64_b32 v[208:209], v130 offset0:24 offset1:28
	ds_read2st64_b32 v[210:211], v130 offset0:32 offset1:36
	ds_read2st64_b32 v[212:213], v130 offset0:40 offset1:44
	ds_read2st64_b32 v[214:215], v130 offset0:48 offset1:52
	ds_read2st64_b32 v[216:217], v130 offset0:56 offset1:60
	ds_read_b32 v218, v174
	s_waitcnt lgkmcnt(0)
	v_add_f32_e32 v128, 0, v202
	v_add_f32_e32 v131, v128, v203
	v_add_f32_e32 v128, v131, v204
	v_add_f32_e32 v131, v128, v205
	v_add_f32_e32 v128, v131, v206
	v_add_f32_e32 v131, v128, v207
	v_add_f32_e32 v128, v131, v208
	v_add_f32_e32 v131, v128, v209
	v_add_f32_e32 v128, v131, v210
	v_add_f32_e32 v131, v128, v211
	v_add_f32_e32 v128, v131, v212
	v_add_f32_e32 v131, v128, v213
	v_add_f32_e32 v128, v131, v214
	v_add_f32_e32 v131, v128, v215
	v_add_f32_e32 v128, v131, v216
	v_add_f32_e32 v128, v128, v217
	v_fmac_f32_e32 v128, v168, v218
	ds_write_b32 v174, v128
